# q64 attention: previous tile's row-sum adds moved from the loop latch to the next tile's K-fragment latency window and first QK MFMAs
# speedup vs baseline: 1.0567x; 1.0007x over previous
; DI int tid() { int t; asm volatile("v_mov_b32 %0, %1" : "=v"(t) : "v"((int)threadIdx.x)); return t; }
; DI void attn_item_q64(const AttnArgs& a, char* smem) {
;     ...
;   const int t = tid(), lane = t & 63, w = __builtin_amdgcn_readfirstlane(t >> 6), r = lane & 31, h = lane >> 5;
;   const int nt = a.n0 + a.n1;
;   u16* qp[2];
;   bf8 qf[2][4];
; #pragma unroll
;   for (int q2 = 0; q2 < 2; ++q2) {
;     qp[q2] = a.qo + (size_t)(w * 64 + q2 * 32 + r) * 1024;
; #pragma unroll
;     for (int ks = 0; ks < 4; ++ks) qf[q2][ks] = *(const bf8*)(qp[q2] + ks * 16 + h * 8);
;   }
;   f32x16 O[2][2];
; #pragma unroll
;   for (int q2 = 0; q2 < 2; ++q2)
; #pragma unroll
;     for (int d = 0; d < 2; ++d)
; #pragma unroll
;       for (int i = 0; i < 16; ++i) O[q2][d][i] = 0.f;
;   float m[2] = {-1e30f, -1e30f}, lsum[2] = {0.f, 0.f};
;   const int srow = t >> 3, sch = (t & 7) ^ ((srow >> 1) & 7);
;   const u16* kg = a.k1 + (size_t)srow * 64 + sch * 8;
;   const u16* vg = a.vt + (size_t)srow * T + sch * 8;
;     ...
;   __syncthreads();
;   ATTN2_ISSUE(0, 0)
;   ATTN2_ISSUE(1, 1)
;   asm volatile("s_waitcnt vmcnt(2)" ::: "memory");
;   __syncthreads();
;   const int sw = (r >> 1) & 7;
;   int koff[4];
; #pragma unroll
;   for (int ks = 0; ks < 4; ++ks) koff[ks] = r * 128 + (((2 * ks + h) ^ sw) << 4);
; DI void phase_attn(const Params& p, int l, char* smem) {
;     ...
;         const int x = id & 7, q = id >> 3, within = q & 15, g = (q >> 4) * 8 + x;
;         const int b = g >> 2, kvh = g & 3, hq = kvh * 4 + (within >> 2), qb = within & 3;
;         a.qo = QO + (size_t)(b * 2048 + qb * 512) * 1024 + hq * 64;
;         a.k1 = Kb + ((size_t)b * 4 + kvh) * T * 64;
;         a.vt = VT + ((size_t)b * 256 + kvh * 64) * T;
;         a.s0 = 0; a.n0 = 32; a.n1 = 4;
.LBB0_420:
	s_and_b64 vcc, exec, s[2:3]
	s_cbranch_vccz .LBB0_411
	s_ashr_i32 s2, s11, 4
	s_and_b32 s0, s11, 4
	s_and_b32 s2, s2, -8
	s_or_b32 s0, s2, s0
	s_lshl_b32 s12, s11, 6
	s_lshl_b32 s3, s0, 9
	s_and_b32 s12, s12, 0x600
	s_or_b32 s12, s3, s12
	s_ashr_i32 s13, s12, 31
	s_ashr_i32 s2, s0, 2
	s_and_b32 s16, s11, 3
	s_lshl_b64 s[12:13], s[12:13], 11
	s_add_u32 s3, s20, s12
	s_addc_u32 s13, s21, s13
	s_lshl_b32 s12, s11, 2
	s_and_b32 s12, s12, 0x180
	s_lshl_b32 s14, s16, 9
	s_or_b32 s12, s14, s12
	s_add_u32 s12, s3, s12
	s_addc_u32 s13, s13, 0
	s_or_b32 s0, s0, s16
	s_ashr_i32 s3, s2, 31
	s_mul_hi_i32 s15, s0, 0x48000
	s_mul_i32 s0, s0, 0x48000
	v_readlane_b32 s18, v235, 50
	v_readlane_b32 s19, v235, 51
	s_add_u32 s14, s18, s0
	s_addc_u32 s15, s19, s15
	s_lshl_b64 s[2:3], s[2:3], 8
	s_lshl_b32 s0, s16, 6
	s_or_b32 s0, s2, s0
	s_mul_i32 s2, s3, 0x1200
	s_mul_hi_u32 s3, s0, 0x1200
	s_add_i32 s3, s3, s2
	s_mulk_i32 s0, 0x1200
	v_readlane_b32 s16, v235, 48
	v_readlane_b32 s17, v235, 49
	s_add_u32 s2, s16, s0
	v_mov_b32 v8, v163
	s_addc_u32 s3, s17, s3
	v_readfirstlane_b32 s0, v8
	v_and_b32_e32 v10, 31, v8
	s_and_b32 s16, s0, 0xffffffc0
	v_or_b32_e32 v2, s16, v10
	v_ashrrev_i32_e32 v3, 31, v2
	v_lshlrev_b64 v[4:5], 11, v[2:3]
	v_or_b32_e32 v2, 32, v2
	v_ashrrev_i32_e32 v3, 31, v2
	v_bfe_u32 v175, v8, 5, 1
	v_lshlrev_b64 v[2:3], 11, v[2:3]
	v_lshl_add_u64 v[166:167], s[12:13], 0, v[4:5]
	v_lshlrev_b32_e32 v0, 4, v175
	v_lshl_add_u64 v[164:165], s[12:13], 0, v[2:3]
	v_lshl_add_u64 v[4:5], v[166:167], 0, v[0:1]
	v_lshl_add_u64 v[2:3], v[164:165], 0, v[0:1]
	global_load_dwordx4 v[130:133], v[4:5], off
	global_load_dwordx4 v[134:137], v[4:5], off offset:32
	global_load_dwordx4 v[138:141], v[4:5], off offset:64
	global_load_dwordx4 v[142:145], v[4:5], off offset:96
	global_load_dwordx4 v[146:149], v[2:3], off
	global_load_dwordx4 v[150:153], v[2:3], off offset:32
	global_load_dwordx4 v[154:157], v[2:3], off offset:64
	global_load_dwordx4 v[158:161], v[2:3], off offset:96
	v_ashrrev_i32_e32 v2, 3, v8
	v_lshrrev_b32_e32 v0, 4, v8
	v_xor_b32_e32 v0, v0, v8
	v_ashrrev_i32_e32 v3, 31, v2
	v_lshlrev_b64 v[4:5], 7, v[2:3]
	v_lshlrev_b32_e32 v0, 4, v0
	v_mov_b64_e32 v[6:7], s[2:3]
	v_lshl_add_u64 v[4:5], s[14:15], 0, v[4:5]
	v_and_b32_e32 v0, 0x70, v0
	v_mad_i64_i32 v[2:3], s[2:3], v2, s77, v[6:7]
	s_lshl_b32 s0, s0, 4
	v_lshl_add_u64 v[4:5], v[4:5], 0, v[0:1]
	s_barrier
	s_and_b32 s0, s0, 0xfffffc00
	s_mov_b32 m0, s0
	s_nop 0
	global_load_lds_dwordx4 v[4:5], off
	s_mov_b64 s[2:3], 0x2000
	v_lshl_add_u64 v[2:3], v[2:3], 0, v[0:1]
	s_add_i32 s12, s0, 0x4000
	s_mov_b32 m0, s12
	s_nop 0
	global_load_lds_dwordx4 v[2:3], off
	v_lshl_add_u64 v[6:7], v[4:5], 0, s[2:3]
	s_add_i32 s2, s0, 0x2000
	s_mov_b32 m0, s2
	s_nop 0
	global_load_lds_dwordx4 v[6:7], off
	s_mov_b64 s[2:3], 0x80
	v_lshl_add_u64 v[6:7], v[2:3], 0, s[2:3]
	v_lshrrev_b32_e32 v0, 1, v8
	s_add_i32 s2, s0, 0x6000
	s_mov_b32 m0, s2
	s_nop 0
	global_load_lds_dwordx4 v[6:7], off
	v_bfe_u32 v6, v8, 1, 3
	v_lshlrev_b32_e32 v7, 7, v10
	v_bitop3_b32 v0, v175, v0, 7 bitop3:0x78
	v_lshl_or_b32 v176, v0, 4, v7
	v_bitop3_b32 v0, v175, v6, 2 bitop3:0x36
	v_lshl_or_b32 v177, v0, 4, v7
	v_bitop3_b32 v0, v175, v6, 4 bitop3:0x36
	v_and_b32_e32 v9, 63, v8
	v_lshl_or_b32 v178, v0, 4, v7
	v_bitop3_b32 v0, v175, v6, 6 bitop3:0x36
	s_mov_b64 s[2:3], 0x100
	v_lshl_or_b32 v179, v0, 4, v7
	v_lshlrev_b32_e32 v0, 2, v9
	v_lshl_add_u64 v[168:169], v[2:3], 0, s[2:3]
	s_mov_b64 s[2:3], 0x4000
	v_mov_b32_e32 v14, v1
	v_mov_b32_e32 v15, v1
	s_waitcnt vmcnt(2)
	v_xor_b32_e32 v173, 0x80, v0
	v_lshl_or_b32 v180, v175, 3, v7
	v_lshlrev_b32_e32 v181, 4, v6
	v_lshl_add_u64 v[170:171], v[4:5], 0, s[2:3]
	v_mov_b32_e32 v0, v1
	v_mov_b32_e32 v2, v1
	v_mov_b32_e32 v3, v1
	v_mov_b32_e32 v4, v1
	v_mov_b32_e32 v5, v1
	v_mov_b32_e32 v6, v1
	v_mov_b32_e32 v7, v1
	v_mov_b32_e32 v8, v1
	v_mov_b32_e32 v9, v1
	v_mov_b32_e32 v10, v1
	v_mov_b32_e32 v11, v1
	v_mov_b32_e32 v12, v1
	v_mov_b32_e32 v13, v1
	v_mov_b64_e32 v[64:65], v[14:15]
	v_mov_b64_e32 v[48:49], v[14:15]
	v_mov_b64_e32 v[32:33], v[14:15]
	v_mov_b64_e32 v[62:63], v[12:13]
	v_mov_b64_e32 v[60:61], v[10:11]
	v_mov_b64_e32 v[58:59], v[8:9]
	v_mov_b64_e32 v[56:57], v[6:7]
	v_mov_b64_e32 v[54:55], v[4:5]
	v_mov_b64_e32 v[52:53], v[2:3]
	v_mov_b64_e32 v[50:51], v[0:1]
	v_mov_b64_e32 v[46:47], v[12:13]
	v_mov_b64_e32 v[44:45], v[10:11]
	v_mov_b64_e32 v[42:43], v[8:9]
	v_mov_b64_e32 v[40:41], v[6:7]
	v_mov_b64_e32 v[38:39], v[4:5]
	v_mov_b64_e32 v[36:37], v[2:3]
	v_mov_b64_e32 v[34:35], v[0:1]
	v_mov_b64_e32 v[30:31], v[12:13]
	v_mov_b64_e32 v[28:29], v[10:11]
	v_mov_b64_e32 v[26:27], v[8:9]
	v_mov_b64_e32 v[24:25], v[6:7]
	v_mov_b64_e32 v[22:23], v[4:5]
	v_mov_b64_e32 v[20:21], v[2:3]
	v_mov_b64_e32 v[18:19], v[0:1]
	v_mov_b64_e32 v[16:17], v[14:15]
	v_xor_b32_e32 v182, 16, v181
	v_xor_b32_e32 v183, 32, v181
	v_xor_b32_e32 v184, 48, v181
	v_xor_b32_e32 v185, 64, v181
	v_xor_b32_e32 v186, 0x50, v181
	v_xor_b32_e32 v187, 0x60, v181
	v_xor_b32_e32 v188, 0x70, v181
	s_mov_b32 s13, 0
	v_mov_b32_e32 v174, 0
	v_mov_b32_e32 v190, 0xf149f2ca
	s_mov_b64 s[2:3], 0
	v_mov_b32_e32 v191, 0xf149f2ca
	v_mov_b32_e32 v189, 0
	v_mov_b64_e32 v[14:15], v[12:13]
	v_mov_b64_e32 v[12:13], v[10:11]
	v_mov_b64_e32 v[10:11], v[8:9]
	v_mov_b64_e32 v[8:9], v[6:7]
	v_mov_b64_e32 v[6:7], v[4:5]
	v_mov_b64_e32 v[4:5], v[2:3]
	v_mov_b64_e32 v[2:3], v[0:1]
	v_mov_b32_e32 v70, 0
	v_mov_b32_e32 v71, 0
	v_mov_b32_e32 v72, 0
	v_mov_b32_e32 v73, 0
	v_mov_b32_e32 v74, 0
	v_mov_b32_e32 v75, 0
	v_mov_b32_e32 v76, 0
	v_mov_b32_e32 v77, 0
	v_mov_b32_e32 v78, 0
	v_mov_b32_e32 v79, 0
	v_mov_b32_e32 v80, 0
	v_mov_b32_e32 v81, 0
	v_mov_b32_e32 v86, 0
	v_mov_b32_e32 v87, 0
	v_mov_b32_e32 v88, 0
	v_mov_b32_e32 v89, 0
	v_mov_b32_e32 v90, 0
	v_mov_b32_e32 v91, 0
	v_mov_b32_e32 v92, 0
	v_mov_b32_e32 v93, 0
	v_mov_b32_e32 v94, 0
	v_mov_b32_e32 v95, 0
	v_mov_b32_e32 v96, 0
	v_mov_b32_e32 v97, 0
	v_mov_b32_e32 v98, 0
	v_mov_b32_e32 v99, 0
	v_mov_b32_e32 v100, 0
	v_mov_b32_e32 v101, 0
	v_mov_b32_e32 v102, 0
	v_mov_b32_e32 v103, 0
	v_mov_b32_e32 v104, 0
	v_mov_b32_e32 v105, 0
	v_mov_b32_e32 v106, 0
	v_mov_b32_e32 v107, 0
	v_mov_b32_e32 v108, 0
	v_mov_b32_e32 v109, 0
	v_mov_b32_e32 v110, 0
	v_mov_b32_e32 v111, 0
	v_mov_b32_e32 v112, 0
	v_mov_b32_e32 v113, 0
	v_mov_b32_e32 v114, 0
	v_mov_b32_e32 v115, 0
	v_mov_b32_e32 v116, 0
	v_mov_b32_e32 v117, 0
	v_mov_b32_e32 v118, 0
	v_mov_b32_e32 v119, 0
	v_mov_b32_e32 v120, 0
	v_mov_b32_e32 v121, 0
	v_mov_b32_e32 v122, 0
	v_mov_b32_e32 v123, 0
	v_mov_b32_e32 v124, 0
	v_mov_b32_e32 v125, 0
	v_mov_b32_e32 v126, 0
	v_mov_b32_e32 v127, 0
	v_mov_b32_e32 v128, 0
	v_mov_b32_e32 v129, 0
	v_mov_b32_e32 v242, 0
	v_mov_b32_e32 v243, 0
	v_mov_b32_e32 v244, 0
	s_barrier
	s_branch .LBB0_423
; DI f32x16 mfma32(bf8 a, bf8 b, f32x16 c) { return __builtin_amdgcn_mfma_f32_32x32x16_bf16(a, b, c, 0, 0, 0); }
; DI float ex2(float x) { return __builtin_amdgcn_exp2f(x); }
; DI float shx(float v, int lane, int mask) { return __int_as_float(__builtin_amdgcn_ds_bpermute((lane ^ mask) << 2, __float_as_int(v))); }
; DI void attn_item_q64(const AttnArgs& a, char* smem) {
;     ...
;     for (int kb = 0; kb < 2; ++kb) {
; #pragma unroll
;       for (int q2 = 0; q2 < 2; ++q2)
; #pragma unroll
;         for (int i = 0; i < 16; ++i) s[q2][kb][i] = 0.f;
; #pragma unroll
;       for (int ks = 0; ks < 4; ++ks) {
;         const bf8 kf = *(const bf8*)(Ks + kb * 32 * 128 + koff[ks]);
; #pragma unroll
;         for (int q2 = 0; q2 < 2; ++q2) s[q2][kb] = mfma32(kf, qf[q2][ks], s[q2][kb]);
;       }
;     }
;     constexpr float SC = 0.125f * LOG2E;
; #pragma unroll
;     for (int q2 = 0; q2 < 2; ++q2) {
;       float mx = -INFINITY;
; #pragma unroll
;       for (int kb = 0; kb < 2; ++kb)
; #pragma unroll
;         for (int i = 0; i < 16; i += 2) mx = fmaxf(fmaxf(mx, s[q2][kb][i]), s[q2][kb][i + 1]);
;       mx = fmaxf(mx, shx(mx, lane, 32)) * SC;
;       const float mn = fmaxf(m[q2], mx);
;       const bool resc = __builtin_amdgcn_ballot_w64(mn != m[q2]) != 0ull;
;       float ps0 = 0.f, ps1 = 0.f;
; #pragma unroll
;       for (int kb = 0; kb < 2; ++kb)
; #pragma unroll
;         for (int i = 0; i < 16; i += 2) {
;           f32x2n v = {s[q2][kb][i], s[q2][kb][i + 1]};
;           v = v * f32x2n{SC, SC} - f32x2n{mn, mn};
;           const float p0 = ex2(v.x), p1 = ex2(v.y);
;           s[q2][kb][i] = p0; s[q2][kb][i + 1] = p1;
;           ps0 += p0; ps1 += p1;
;         }
;       if (resc) {
;         const float alpha = ex2(m[q2] - mn);
;         m[q2] = mn;
;         lsum[q2] *= alpha;
; #pragma unroll
;         for (int d = 0; d < 2; ++d)
; #pragma unroll
;           for (int i = 0; i < 16; ++i) O[q2][d][i] *= alpha;
;       }
;       lsum[q2] += ps0 + ps1;
.Lq64_xadds:
	v_add_f32_e32 v66, 0, v66
	v_add_f32_e32 v67, 0, v67
	v_add_f32_e32 v66, v68, v66
	v_add_f32_e32 v67, v69, v67
	v_add_f32_e32 v66, v70, v66
	v_add_f32_e32 v67, v71, v67
	v_add_f32_e32 v66, v72, v66
	v_add_f32_e32 v67, v73, v67
	v_add_f32_e32 v66, v74, v66
	v_add_f32_e32 v67, v75, v67
	v_add_f32_e32 v66, v76, v66
	v_add_f32_e32 v67, v77, v67
	v_add_f32_e32 v66, v78, v66
	v_add_f32_e32 v67, v79, v67
	v_add_f32_e32 v66, v80, v66
	v_add_f32_e32 v67, v81, v67
	v_add_f32_e32 v66, v82, v66
	v_add_f32_e32 v67, v83, v67
	v_add_f32_e32 v66, v84, v66
	v_add_f32_e32 v67, v85, v67
	v_add_f32_e32 v66, v86, v66
	v_add_f32_e32 v67, v87, v67
	v_add_f32_e32 v66, v88, v66
	v_add_f32_e32 v67, v89, v67
	v_add_f32_e32 v66, v90, v66
	v_add_f32_e32 v67, v91, v67
	v_add_f32_e32 v66, v92, v66
	v_add_f32_e32 v67, v93, v67
	v_add_f32_e32 v66, v94, v66
	v_add_f32_e32 v67, v95, v67
	v_add_f32_e32 v66, v96, v66
	v_add_f32_e32 v67, v97, v67
	v_add_f32_e32 v66, v66, v67
	v_add_f32_e32 v174, v66, v174
	v_add_f32_e32 v66, 0, v98
	v_add_f32_e32 v67, 0, v99
	v_add_f32_e32 v66, v100, v66
	v_add_f32_e32 v67, v101, v67
	v_add_f32_e32 v66, v102, v66
	v_add_f32_e32 v67, v103, v67
	v_add_f32_e32 v66, v104, v66
	v_add_f32_e32 v67, v105, v67
	v_add_f32_e32 v66, v106, v66
	v_add_f32_e32 v67, v107, v67
	v_add_f32_e32 v66, v108, v66
	v_add_f32_e32 v67, v109, v67
	v_add_f32_e32 v66, v110, v66
	v_add_f32_e32 v67, v111, v67
	v_add_f32_e32 v66, v112, v66
	v_add_f32_e32 v67, v113, v67
	v_add_f32_e32 v66, v114, v66
	v_add_f32_e32 v67, v115, v67
	v_add_f32_e32 v66, v116, v66
	v_add_f32_e32 v67, v117, v67
	v_add_f32_e32 v66, v118, v66
	v_add_f32_e32 v67, v119, v67
	v_add_f32_e32 v66, v120, v66
	v_add_f32_e32 v67, v121, v67
	v_add_f32_e32 v66, v122, v66
	v_add_f32_e32 v67, v123, v67
	v_add_f32_e32 v66, v124, v66
	v_add_f32_e32 v67, v125, v67
	v_add_f32_e32 v66, v126, v66
	v_add_f32_e32 v67, v127, v67
	v_add_f32_e32 v0, v0, v66
	v_add_f32_e32 v66, v128, v67
	v_add_f32_e32 v0, v0, v66
	v_add_f32_e32 v189, v0, v189
	s_branch .LBB0_410
.LBB0_422:
	s_add_i32 s13, s13, 1
	s_add_u32 s2, s2, 0x2000
	s_addc_u32 s3, s3, 0
	s_mov_b64 s[14:15], 0x80
	s_cmp_lg_u32 s2, 0x48000
	v_lshl_add_u64 v[168:169], v[168:169], 0, s[14:15]
	s_cbranch_scc0 .Lq64_xadds
	v_add_f32_e32 v242, v66, v68
	v_add_f32_e32 v243, v67, v69
	v_add_f32_e32 v242, v82, v242
	v_add_f32_e32 v243, v83, v243
	v_add_f32_e32 v242, v84, v242
	v_add_f32_e32 v243, v85, v243
	v_add_f32_e32 v244, v0, v98
.LBB0_423:
	s_and_b32 s14, s2, 0x2000
	v_or_b32_e32 v0, s14, v176
	s_waitcnt vmcnt(19)
	ds_read_b128 v[66:69], v0
	v_or_b32_e32 v172, s14, v177
	s_waitcnt vmcnt(17)
	ds_read_b128 v[82:85], v172
	v_or_b32_e32 v196, s14, v178
	v_or_b32_e32 v197, s14, v179
	ds_read_b128 v[192:195], v172 offset:4096
	v_add_f32_e32 v245, v99, v101
	v_add_f32_e32 v244, v100, v244
	v_add_f32_e32 v244, v102, v244
	v_add_f32_e32 v244, v104, v244
	v_add_f32_e32 v244, v106, v244
	v_add_f32_e32 v244, v108, v244
	v_add_f32_e32 v244, v110, v244
	v_add_f32_e32 v244, v112, v244
	v_add_f32_e32 v245, v103, v245
	v_add_f32_e32 v245, v105, v245
	v_add_f32_e32 v245, v107, v245
	v_add_f32_e32 v245, v109, v245
	v_add_f32_e32 v245, v111, v245
	v_add_f32_e32 v245, v113, v245
	v_add_f32_e32 v242, v70, v242
	v_add_f32_e32 v242, v72, v242
	v_add_f32_e32 v242, v74, v242
	v_add_f32_e32 v242, v76, v242
	v_add_f32_e32 v242, v78, v242
	v_add_f32_e32 v242, v80, v242
	v_add_f32_e32 v243, v71, v243
	v_add_f32_e32 v243, v73, v243
	v_add_f32_e32 v243, v75, v243
	v_add_f32_e32 v243, v77, v243
	v_add_f32_e32 v243, v79, v243
	v_add_f32_e32 v243, v81, v243
	s_waitcnt vmcnt(7) lgkmcnt(2)
	v_mfma_f32_32x32x16_bf16 v[98:113], v[66:69], v[130:133], 0
	s_waitcnt vmcnt(3)
	v_mfma_f32_32x32x16_bf16 v[66:81], v[66:69], v[146:149], 0
	v_add_f32_e32 v244, v114, v244
	v_add_f32_e32 v244, v116, v244
	v_add_f32_e32 v244, v118, v244
	v_add_f32_e32 v244, v120, v244
	v_add_f32_e32 v244, v122, v244
	s_waitcnt lgkmcnt(1)
	v_mfma_f32_32x32x16_bf16 v[98:113], v[82:85], v[134:137], v[98:113]
	v_add_f32_e32 v244, v124, v244
	v_add_f32_e32 v244, v126, v244
	v_add_f32_e32 v245, v115, v245
	v_add_f32_e32 v245, v117, v245
	s_waitcnt vmcnt(2)
	v_mfma_f32_32x32x16_bf16 v[66:81], v[82:85], v[150:153], v[66:81]
	v_add_f32_e32 v245, v119, v245
	v_add_f32_e32 v245, v121, v245
	v_add_f32_e32 v245, v123, v245
	v_add_f32_e32 v245, v125, v245
	ds_read_b128 v[82:85], v196
	s_waitcnt lgkmcnt(0)
	v_mfma_f32_32x32x16_bf16 v[98:113], v[82:85], v[138:141], v[98:113]
	v_add_f32_e32 v245, v127, v245
	v_add_f32_e32 v245, v128, v245
	v_add_f32_e32 v242, v86, v242
	v_add_f32_e32 v242, v88, v242
	v_add_f32_e32 v242, v90, v242
	s_waitcnt vmcnt(1)
	v_mfma_f32_32x32x16_bf16 v[66:81], v[82:85], v[154:157], v[66:81]
	v_add_f32_e32 v242, v92, v242
	v_add_f32_e32 v242, v94, v242
	v_add_f32_e32 v242, v96, v242
	v_add_f32_e32 v243, v87, v243
	ds_read_b128 v[82:85], v197
	s_waitcnt lgkmcnt(0)
	v_mfma_f32_32x32x16_bf16 v[98:113], v[82:85], v[142:145], v[98:113]
	v_add_f32_e32 v243, v89, v243
	v_add_f32_e32 v243, v91, v243
	v_add_f32_e32 v243, v93, v243
	v_add_f32_e32 v243, v95, v243
	v_add_f32_e32 v243, v97, v243
	s_waitcnt vmcnt(0)
	v_mfma_f32_32x32x16_bf16 v[66:81], v[82:85], v[158:161], v[66:81]
	ds_read_b128 v[82:85], v0 offset:4096
	v_add_f32_e32 v242, v242, v243
	v_add_f32_e32 v174, v242, v174
	v_add_f32_e32 v244, v244, v245
	v_add_f32_e32 v189, v244, v189
	s_nop 8
	v_max3_f32 v0, v98, s33, v99
	v_max3_f32 v0, v0, v100, v101
	v_max3_f32 v0, v0, v102, v103
	v_max3_f32 v0, v0, v104, v105
	v_max3_f32 v0, v0, v106, v107
	v_max3_f32 v0, v0, v108, v109
	s_waitcnt lgkmcnt(0)
	v_mfma_f32_32x32x16_bf16 v[114:129], v[82:85], v[130:133], 0
	v_max3_f32 v0, v0, v110, v111
	v_max3_f32 v0, v0, v112, v113
	v_mfma_f32_32x32x16_bf16 v[82:97], v[82:85], v[146:149], 0
	v_mfma_f32_32x32x16_bf16 v[114:129], v[192:195], v[134:137], v[114:129]
	v_mfma_f32_32x32x16_bf16 v[82:97], v[192:195], v[150:153], v[82:97]
	ds_read_b128 v[192:195], v196 offset:4096
	s_waitcnt lgkmcnt(0)
	v_mfma_f32_32x32x16_bf16 v[114:129], v[192:195], v[138:141], v[114:129]
	v_mfma_f32_32x32x16_bf16 v[82:97], v[192:195], v[154:157], v[82:97]
	ds_read_b128 v[192:195], v197 offset:4096
	s_waitcnt lgkmcnt(0)
	v_mfma_f32_32x32x16_bf16 v[114:129], v[192:195], v[142:145], v[114:129]
	v_mfma_f32_32x32x16_bf16 v[82:97], v[192:195], v[158:161], v[82:97]
	s_nop 10
	v_max3_f32 v0, v0, v114, v115
	v_max3_f32 v0, v0, v116, v117
	v_max3_f32 v0, v0, v118, v119
	v_max3_f32 v0, v0, v120, v121
	v_max3_f32 v0, v0, v122, v123
	v_max3_f32 v0, v0, v124, v125
	v_max3_f32 v0, v0, v126, v127
	v_max3_f32 v0, v0, v128, v129
	v_mul_f32_e32 v172, 0x3e38aa3b, v0
	v_sub_f32_e32 v172, v172, v191
	v_cmp_lt_f32_e32 vcc, 8.0, v172
	s_cbranch_vccnz .Llz_2
	v_mov_b32_e32 v0, v191
	s_branch .LBB0_425
